# P2 stage E tail: pack/store loops of the solved columns read LDS in double-buffered 8-row batches
# speedup vs baseline: 1.0099x; 1.0008x over previous
.LBB0_446:
	s_mov_b64 s[6:7], exec
	s_and_b64 exec, s[6:7], s[46:47]
	s_cbranch_execz .Lpk_u
	v_lshl_add_u64 v[0:1], s[96:97], 0, v[86:87]
	ds_read_b32 v2, v132
	ds_read_b32 v3, v132 offset:528
	ds_read_b32 v4, v132 offset:1056
	ds_read_b32 v5, v132 offset:1584
	ds_read_b32 v6, v132 offset:2112
	ds_read_b32 v7, v132 offset:2640
	ds_read_b32 v8, v132 offset:3168
	ds_read_b32 v9, v132 offset:3696
	ds_read_b32 v240, v132 offset:4224
	ds_read_b32 v241, v132 offset:4752
	ds_read_b32 v242, v132 offset:5280
	ds_read_b32 v243, v132 offset:5808
	ds_read_b32 v244, v132 offset:6336
	ds_read_b32 v245, v132 offset:6864
	ds_read_b32 v246, v132 offset:7392
	ds_read_b32 v247, v132 offset:7920
	s_waitcnt lgkmcnt(8)
	v_cvt_pk_bf16_f32 v20, v2, v3
	v_cvt_pk_bf16_f32 v21, v4, v5
	v_cvt_pk_bf16_f32 v22, v6, v7
	v_cvt_pk_bf16_f32 v23, v8, v9
	global_store_short v[0:1], v20, off
	global_store_short_d16_hi v[0:1], v20, off offset:272
	global_store_short v[0:1], v21, off offset:544
	global_store_short_d16_hi v[0:1], v21, off offset:816
	global_store_short v[0:1], v22, off offset:1088
	global_store_short_d16_hi v[0:1], v22, off offset:1360
	global_store_short v[0:1], v23, off offset:1632
	global_store_short_d16_hi v[0:1], v23, off offset:1904
	ds_read_b32 v2, v132 offset:8448
	ds_read_b32 v3, v132 offset:8976
	ds_read_b32 v4, v132 offset:9504
	ds_read_b32 v5, v132 offset:10032
	ds_read_b32 v6, v132 offset:10560
	ds_read_b32 v7, v132 offset:11088
	ds_read_b32 v8, v132 offset:11616
	ds_read_b32 v9, v132 offset:12144
	s_waitcnt lgkmcnt(8)
	v_cvt_pk_bf16_f32 v20, v240, v241
	v_cvt_pk_bf16_f32 v21, v242, v243
	v_cvt_pk_bf16_f32 v22, v244, v245
	v_cvt_pk_bf16_f32 v23, v246, v247
	global_store_short v[0:1], v20, off offset:2176
	global_store_short_d16_hi v[0:1], v20, off offset:2448
	global_store_short v[0:1], v21, off offset:2720
	global_store_short_d16_hi v[0:1], v21, off offset:2992
	global_store_short v[0:1], v22, off offset:3264
	global_store_short_d16_hi v[0:1], v22, off offset:3536
	global_store_short v[0:1], v23, off offset:3808
	global_store_short_d16_hi v[0:1], v23, off offset:4080
	ds_read_b32 v240, v132 offset:12672
	ds_read_b32 v241, v132 offset:13200
	ds_read_b32 v242, v132 offset:13728
	ds_read_b32 v243, v132 offset:14256
	ds_read_b32 v244, v132 offset:14784
	ds_read_b32 v245, v132 offset:15312
	ds_read_b32 v246, v132 offset:15840
	ds_read_b32 v247, v132 offset:16368
	s_waitcnt lgkmcnt(8)
	v_add_co_u32_e32 v28, vcc, 0x1100, v0
	s_nop 1
	v_addc_co_u32_e32 v29, vcc, 0, v1, vcc
	v_cvt_pk_bf16_f32 v20, v2, v3
	v_cvt_pk_bf16_f32 v21, v4, v5
	v_cvt_pk_bf16_f32 v22, v6, v7
	v_cvt_pk_bf16_f32 v23, v8, v9
	global_store_short v[28:29], v20, off
	global_store_short_d16_hi v[28:29], v20, off offset:272
	global_store_short v[28:29], v21, off offset:544
	global_store_short_d16_hi v[28:29], v21, off offset:816
	global_store_short v[28:29], v22, off offset:1088
	global_store_short_d16_hi v[28:29], v22, off offset:1360
	global_store_short v[28:29], v23, off offset:1632
	global_store_short_d16_hi v[28:29], v23, off offset:1904
	ds_read_b32 v2, v132 offset:16896
	ds_read_b32 v3, v132 offset:17424
	ds_read_b32 v4, v132 offset:17952
	ds_read_b32 v5, v132 offset:18480
	ds_read_b32 v6, v132 offset:19008
	ds_read_b32 v7, v132 offset:19536
	ds_read_b32 v8, v132 offset:20064
	ds_read_b32 v9, v132 offset:20592
	s_waitcnt lgkmcnt(8)
	v_cvt_pk_bf16_f32 v20, v240, v241
	v_cvt_pk_bf16_f32 v21, v242, v243
	v_cvt_pk_bf16_f32 v22, v244, v245
	v_cvt_pk_bf16_f32 v23, v246, v247
	global_store_short v[28:29], v20, off offset:2176
	global_store_short_d16_hi v[28:29], v20, off offset:2448
	global_store_short v[28:29], v21, off offset:2720
	global_store_short_d16_hi v[28:29], v21, off offset:2992
	global_store_short v[28:29], v22, off offset:3264
	global_store_short_d16_hi v[28:29], v22, off offset:3536
	global_store_short v[28:29], v23, off offset:3808
	global_store_short_d16_hi v[28:29], v23, off offset:4080
	ds_read_b32 v240, v132 offset:21120
	ds_read_b32 v241, v132 offset:21648
	ds_read_b32 v242, v132 offset:22176
	ds_read_b32 v243, v132 offset:22704
	ds_read_b32 v244, v132 offset:23232
	ds_read_b32 v245, v132 offset:23760
	ds_read_b32 v246, v132 offset:24288
	ds_read_b32 v247, v132 offset:24816
	s_waitcnt lgkmcnt(8)
	v_add_co_u32_e32 v28, vcc, 0x2200, v0
	s_nop 1
	v_addc_co_u32_e32 v29, vcc, 0, v1, vcc
	v_cvt_pk_bf16_f32 v20, v2, v3
	v_cvt_pk_bf16_f32 v21, v4, v5
	v_cvt_pk_bf16_f32 v22, v6, v7
	v_cvt_pk_bf16_f32 v23, v8, v9
	global_store_short v[28:29], v20, off
	global_store_short_d16_hi v[28:29], v20, off offset:272
	global_store_short v[28:29], v21, off offset:544
	global_store_short_d16_hi v[28:29], v21, off offset:816
	global_store_short v[28:29], v22, off offset:1088
	global_store_short_d16_hi v[28:29], v22, off offset:1360
	global_store_short v[28:29], v23, off offset:1632
	global_store_short_d16_hi v[28:29], v23, off offset:1904
	ds_read_b32 v2, v132 offset:25344
	ds_read_b32 v3, v132 offset:25872
	ds_read_b32 v4, v132 offset:26400
	ds_read_b32 v5, v132 offset:26928
	ds_read_b32 v6, v132 offset:27456
	ds_read_b32 v7, v132 offset:27984
	ds_read_b32 v8, v132 offset:28512
	ds_read_b32 v9, v132 offset:29040
	s_waitcnt lgkmcnt(8)
	v_cvt_pk_bf16_f32 v20, v240, v241
	v_cvt_pk_bf16_f32 v21, v242, v243
	v_cvt_pk_bf16_f32 v22, v244, v245
	v_cvt_pk_bf16_f32 v23, v246, v247
	global_store_short v[28:29], v20, off offset:2176
	global_store_short_d16_hi v[28:29], v20, off offset:2448
	global_store_short v[28:29], v21, off offset:2720
	global_store_short_d16_hi v[28:29], v21, off offset:2992
	global_store_short v[28:29], v22, off offset:3264
	global_store_short_d16_hi v[28:29], v22, off offset:3536
	global_store_short v[28:29], v23, off offset:3808
	global_store_short_d16_hi v[28:29], v23, off offset:4080
	ds_read_b32 v240, v132 offset:29568
	ds_read_b32 v241, v132 offset:30096
	ds_read_b32 v242, v132 offset:30624
	ds_read_b32 v243, v132 offset:31152
	ds_read_b32 v244, v132 offset:31680
	ds_read_b32 v245, v132 offset:32208
	ds_read_b32 v246, v132 offset:32736
	ds_read_b32 v247, v132 offset:33264
	s_waitcnt lgkmcnt(8)
	v_add_co_u32_e32 v28, vcc, 0x3300, v0
	s_nop 1
	v_addc_co_u32_e32 v29, vcc, 0, v1, vcc
	v_cvt_pk_bf16_f32 v20, v2, v3
	v_cvt_pk_bf16_f32 v21, v4, v5
	v_cvt_pk_bf16_f32 v22, v6, v7
	v_cvt_pk_bf16_f32 v23, v8, v9
	global_store_short v[28:29], v20, off
	global_store_short_d16_hi v[28:29], v20, off offset:272
	global_store_short v[28:29], v21, off offset:544
	global_store_short_d16_hi v[28:29], v21, off offset:816
	global_store_short v[28:29], v22, off offset:1088
	global_store_short_d16_hi v[28:29], v22, off offset:1360
	global_store_short v[28:29], v23, off offset:1632
	global_store_short_d16_hi v[28:29], v23, off offset:1904
	s_waitcnt lgkmcnt(0)
	v_cvt_pk_bf16_f32 v20, v240, v241
	v_cvt_pk_bf16_f32 v21, v242, v243
	v_cvt_pk_bf16_f32 v22, v244, v245
	v_cvt_pk_bf16_f32 v23, v246, v247
	global_store_short v[28:29], v20, off offset:2176
	global_store_short_d16_hi v[28:29], v20, off offset:2448
	global_store_short v[28:29], v21, off offset:2720
	global_store_short_d16_hi v[28:29], v21, off offset:2992
	global_store_short v[28:29], v22, off offset:3264
	global_store_short_d16_hi v[28:29], v22, off offset:3536
	global_store_short v[28:29], v23, off offset:3808
	global_store_short_d16_hi v[28:29], v23, off offset:4080
.Lpk_u:
	s_andn2_b64 exec, s[6:7], s[46:47]
	s_cbranch_execz .LBB0_233
	v_lshl_add_u64 v[0:1], v[104:105], 0, s[82:83]
	ds_read_b32 v2, v132
	ds_read_b32 v3, v132 offset:528
	ds_read_b32 v4, v132 offset:1056
	ds_read_b32 v5, v132 offset:1584
	ds_read_b32 v6, v132 offset:2112
	ds_read_b32 v7, v132 offset:2640
	ds_read_b32 v8, v132 offset:3168
	ds_read_b32 v9, v132 offset:3696
	ds_read_b32 v240, v132 offset:4224
	ds_read_b32 v241, v132 offset:4752
	ds_read_b32 v242, v132 offset:5280
	ds_read_b32 v243, v132 offset:5808
	ds_read_b32 v244, v132 offset:6336
	ds_read_b32 v245, v132 offset:6864
	ds_read_b32 v246, v132 offset:7392
	ds_read_b32 v247, v132 offset:7920
	s_waitcnt lgkmcnt(8)
	v_cvt_pk_bf16_f32 v20, v2, v3
	v_cvt_pk_bf16_f32 v21, v4, v5
	v_cvt_pk_bf16_f32 v22, v6, v7
	v_cvt_pk_bf16_f32 v23, v8, v9
	global_store_dwordx4 v[0:1], v[20:23], off
	ds_read_b32 v2, v132 offset:8448
	ds_read_b32 v3, v132 offset:8976
	ds_read_b32 v4, v132 offset:9504
	ds_read_b32 v5, v132 offset:10032
	ds_read_b32 v6, v132 offset:10560
	ds_read_b32 v7, v132 offset:11088
	ds_read_b32 v8, v132 offset:11616
	ds_read_b32 v9, v132 offset:12144
	s_waitcnt lgkmcnt(8)
	v_cvt_pk_bf16_f32 v20, v240, v241
	v_cvt_pk_bf16_f32 v21, v242, v243
	v_cvt_pk_bf16_f32 v22, v244, v245
	v_cvt_pk_bf16_f32 v23, v246, v247
	global_store_dwordx4 v[0:1], v[20:23], off offset:16
	ds_read_b32 v240, v132 offset:12672
	ds_read_b32 v241, v132 offset:13200
	ds_read_b32 v242, v132 offset:13728
	ds_read_b32 v243, v132 offset:14256
	ds_read_b32 v244, v132 offset:14784
	ds_read_b32 v245, v132 offset:15312
	ds_read_b32 v246, v132 offset:15840
	ds_read_b32 v247, v132 offset:16368
	s_waitcnt lgkmcnt(8)
	v_cvt_pk_bf16_f32 v20, v2, v3
	v_cvt_pk_bf16_f32 v21, v4, v5
	v_cvt_pk_bf16_f32 v22, v6, v7
	v_cvt_pk_bf16_f32 v23, v8, v9
	global_store_dwordx4 v[0:1], v[20:23], off offset:32
	ds_read_b32 v2, v132 offset:16896
	ds_read_b32 v3, v132 offset:17424
	ds_read_b32 v4, v132 offset:17952
	ds_read_b32 v5, v132 offset:18480
	ds_read_b32 v6, v132 offset:19008
	ds_read_b32 v7, v132 offset:19536
	ds_read_b32 v8, v132 offset:20064
	ds_read_b32 v9, v132 offset:20592
	s_waitcnt lgkmcnt(8)
	v_cvt_pk_bf16_f32 v20, v240, v241
	v_cvt_pk_bf16_f32 v21, v242, v243
	v_cvt_pk_bf16_f32 v22, v244, v245
	v_cvt_pk_bf16_f32 v23, v246, v247
	global_store_dwordx4 v[0:1], v[20:23], off offset:48
	ds_read_b32 v240, v132 offset:21120
	ds_read_b32 v241, v132 offset:21648
	ds_read_b32 v242, v132 offset:22176
	ds_read_b32 v243, v132 offset:22704
	ds_read_b32 v244, v132 offset:23232
	ds_read_b32 v245, v132 offset:23760
	ds_read_b32 v246, v132 offset:24288
	ds_read_b32 v247, v132 offset:24816
	s_waitcnt lgkmcnt(8)
	v_cvt_pk_bf16_f32 v20, v2, v3
	v_cvt_pk_bf16_f32 v21, v4, v5
	v_cvt_pk_bf16_f32 v22, v6, v7
	v_cvt_pk_bf16_f32 v23, v8, v9
	global_store_dwordx4 v[0:1], v[20:23], off offset:64
	ds_read_b32 v2, v132 offset:25344
	ds_read_b32 v3, v132 offset:25872
	ds_read_b32 v4, v132 offset:26400
	ds_read_b32 v5, v132 offset:26928
	ds_read_b32 v6, v132 offset:27456
	ds_read_b32 v7, v132 offset:27984
	ds_read_b32 v8, v132 offset:28512
	ds_read_b32 v9, v132 offset:29040
	s_waitcnt lgkmcnt(8)
	v_cvt_pk_bf16_f32 v20, v240, v241
	v_cvt_pk_bf16_f32 v21, v242, v243
	v_cvt_pk_bf16_f32 v22, v244, v245
	v_cvt_pk_bf16_f32 v23, v246, v247
	global_store_dwordx4 v[0:1], v[20:23], off offset:80
	ds_read_b32 v240, v132 offset:29568
	ds_read_b32 v241, v132 offset:30096
	ds_read_b32 v242, v132 offset:30624
	ds_read_b32 v243, v132 offset:31152
	ds_read_b32 v244, v132 offset:31680
	ds_read_b32 v245, v132 offset:32208
	ds_read_b32 v246, v132 offset:32736
	ds_read_b32 v247, v132 offset:33264
	s_waitcnt lgkmcnt(8)
	v_cvt_pk_bf16_f32 v20, v2, v3
	v_cvt_pk_bf16_f32 v21, v4, v5
	v_cvt_pk_bf16_f32 v22, v6, v7
	v_cvt_pk_bf16_f32 v23, v8, v9
	global_store_dwordx4 v[0:1], v[20:23], off offset:96
	s_waitcnt lgkmcnt(0)
	v_cvt_pk_bf16_f32 v20, v240, v241
	v_cvt_pk_bf16_f32 v21, v242, v243
	v_cvt_pk_bf16_f32 v22, v244, v245
	v_cvt_pk_bf16_f32 v23, v246, v247
	global_store_dwordx4 v[0:1], v[20:23], off offset:112
	s_branch .LBB0_233
